# odd row-block classes start P8 about 10 us late (back chain only) on top of the hidmap + adaLN-unroll version
# baseline (speedup 1.0000x reference)
; #define LAS __attribute__((address_space(3)))
; #define lane (lane_now())
; __device__ __forceinline__ void rwkv_out_ch(const Params& p, LAS unsigned char* ldsw, int ch, int lane) {
;     const int bh = ch >> 7, c = ch & 127, b = bh >> 3, h = bh & 7, fr = lane & 15, fq = lane >> 4;
;     const h16* base = (const h16*)(p.ws + WS_SC) + ((size_t)bh * SEQ + (size_t)c * 64) * 384;
;     const bf16_t* G = (const bf16_t*)(p.ws + WS_G); const float* SS = (const float*)(p.ws + WS_SS); bf16_t* MIX = (bf16_t*)(p.ws + WS_MIX);
;     LAS bf16_t* stg = (LAS bf16_t*)ldsw;
;     bf16x8 sf[4][2]; f32x4 lg[4], lb[4];
; #pragma unroll
;     for (int nt = 0; nt < 4; ++nt) {
; #pragma unroll
;         for (int ks = 0; ks < 2; ++ks) sf[nt][ks] = *(const bf16x8*)(base + (size_t)((16 * nt + fr) * 6 + 1) * 64 + ks * 32 + fq * 8);
;         const int cc = h * 64 + 16 * fq + 4 * nt; lg[nt] = *(const f32x4*)(p.lnx_g + cc); lb[nt] = *(const f32x4*)(p.lnx_b + cc);
;     }
;     bf16x8 rbfB[2][2]; f32x4 y0B[2][4]; u32x2 gB[2][4]; h16x4 vB[2][4]; float bonB[2];
; __global__ void __launch_bounds__(512, 2) mega_fwd(Params p) {
;     ...
;     { const int lane9 = lane; LAS unsigned char* ldsw = lds + wave * (16 * MS * 2); for (int it = gw; it < 32 * 128; it += ngw) rwkv_out_ch(p, ldsw, it, lane9); }
.LBB0_1096:
	v_readlane_b32 s0, v244, 31
	v_readlane_b32 s1, v244, 32
	s_andn2_b64 vcc, exec, s[0:1]
	s_waitcnt lgkmcnt(0)
	s_barrier
	v_mbcnt_lo_u32_b32 v0, -1, 0
	v_mbcnt_hi_u32_b32 v0, -1, v0
	s_cbranch_vccnz .LBB0_1099
	v_and_b32_e32 v6, 64, v166
	v_xor_b32_e32 v1, 16, v166
	v_add_u32_e32 v6, 64, v6
	v_cmp_lt_i32_e32 vcc, v1, v6
	s_add_u32 s0, s92, 0x4b00000
	s_mul_i32 s4, s69, 0x900
	v_cndmask_b32_e32 v1, v166, v1, vcc
	v_lshlrev_b32_e32 v151, 2, v1
	v_xor_b32_e32 v1, 32, v166
	v_cmp_lt_i32_e32 vcc, v1, v6
	v_and_b32_e32 v85, 15, v0
	v_and_b32_e32 v103, -16, v0
	v_cndmask_b32_e32 v1, v166, v1, vcc
	s_addc_u32 s1, s93, 0
	s_add_i32 s4, s4, 0
	v_ashrrev_i32_e32 v2, 4, v0
	v_lshlrev_b32_e32 v152, 2, v1
	s_movk_i32 s5, 0x90
	v_mul_u32_u24_e32 v1, 0x90, v85
	v_lshlrev_b32_e32 v6, 1, v103
	v_ashrrev_i32_e32 v66, 2, v0
	v_lshlrev_b32_e32 v0, 5, v0
	v_add3_u32 v153, s4, v1, v6
	v_mul_lo_u32 v1, v66, s5
	v_and_b32_e32 v0, 0x60, v0
	v_mul_u32_u24_e32 v3, 0x180, v85
	v_add3_u32 v154, s4, v1, v0
	v_mov_b32_e32 v1, 0
	v_lshl_add_u64 v[68:69], s[96:97], 0, v[0:1]
	v_lshlrev_b32_e32 v0, 1, v3
	v_ashrrev_i32_e32 v3, 31, v2
	v_lshlrev_b32_e32 v4, 2, v2
	v_lshlrev_b64 v[72:73], 3, v[2:3]
	v_lshlrev_b32_e32 v64, 3, v2
	v_ashrrev_i32_e32 v5, 31, v4
	v_sub_co_u32_e32 v74, vcc, 0, v72
	s_lshl_b32 s4, s68, 9
	s_mov_b32 s9, 0
	v_ashrrev_i32_e32 v65, 31, v64
	v_or_b32_e32 v150, 16, v85
	v_ashrrev_i32_e32 v67, 31, v66
	v_or_b32_e32 v155, 32, v85
	v_or_b32_e32 v156, 48, v85
	v_lshl_add_u64 v[70:71], s[6:7], 0, v[0:1]
	v_subb_co_u32_e32 v75, vcc, 0, v73, vcc
	s_add_i32 s28, s4, s86
	s_lshl_b32 s29, s94, 9
	v_mov_b32_e32 v157, 0x300
	s_mov_b64 s[6:7], 0x3000
	s_mov_b64 s[10:11], 0x6080
	s_movk_i32 s30, 0x6000
	s_mov_b64 s[12:13], 0x9080
	s_mov_b32 s31, 0x9000
	v_lshlrev_b64 v[76:77], 1, v[4:5]
	v_mov_b32_e32 v158, 0x3a27c5ac
	s_mov_b32 s34, 0x800000
	s_mov_b64 s[14:15], 0x6000
	s_mov_b64 s[16:17], 0x9000
	s_mov_b32 s35, s78
	s_mov_b32 s101, s84
	s_mov_b32 s98, 0x1000
	v_readlane_b32 s99, v244, 61
	s_cmp_eq_u32 s99, 0
	s_cbranch_scc1 .Lxo_keep
	s_bitcmp1_b32 s78, 3
	s_cbranch_scc0 .Lstg8_done
	s_movk_i32 s99, 3
